# P5/P10 sample-row GEMM (K=4096): coalesced operand loads + ds_bpermute to the MFMA lane layout, batched with counted waits
# speedup vs baseline: 1.0164x; 1.0164x over previous
.LBB0_1088:
	s_or_b64 exec, exec, s[42:43]
	v_add_u32_e32 v4, s22, v25
	v_ashrrev_i32_e32 v5, 31, v4
	v_or_b32_e32 v14, s21, v20
	v_lshlrev_b64 v[4:5], 13, v[4:5]
	v_ashrrev_i32_e32 v15, 31, v14
	v_lshl_add_u64 v[16:17], v[6:7], 0, v[4:5]
	v_lshlrev_b64 v[14:15], 13, v[14:15]
	v_add_co_u32_e32 v4, vcc, 0x20000, v16
	v_lshl_add_u64 v[14:15], v[8:9], 0, v[14:15]
	s_nop 0
	v_addc_co_u32_e32 v5, vcc, 0, v17, vcc
	v_add_co_u32_e32 v18, vcc, 0x20000, v14
	s_nop 1
	v_addc_co_u32_e32 v19, vcc, 0, v15, vcc
	v_and_b32_e32 v42, 63, v204
	v_lshrrev_b32_e32 v43, 2, v42
	v_and_b32_e32 v44, 15, v42
	v_lshlrev_b32_e32 v199, 2, v44
	v_lshrrev_b32_e32 v45, 4, v42
	v_add_u32_e32 v199, v199, v45
	v_lshlrev_b32_e32 v199, 2, v199
	v_sub_u32_e32 v43, v43, v44
	v_lshlrev_b32_e32 v43, 13, v43
	v_and_b32_e32 v44, 3, v42
	v_lshlrev_b32_e32 v44, 4, v44
	v_and_b32_e32 v45, 48, v42
	v_sub_u32_e32 v44, v44, v45
	v_add_u32_e32 v42, v43, v44
	v_ashrrev_i32_e32 v43, 31, v42
	v_lshl_add_u64 v[14:15], v[14:15], 0, v[42:43]
	v_lshl_add_u64 v[18:19], v[18:19], 0, v[42:43]
	v_lshl_add_u64 v[16:17], v[16:17], 0, v[42:43]
	v_lshl_add_u64 v[4:5], v[4:5], 0, v[42:43]
	global_load_dwordx4 v[64:67], v[14:15], off
	global_load_dwordx4 v[68:71], v[18:19], off
	global_load_dwordx4 v[72:75], v[16:17], off
	global_load_dwordx4 v[76:79], v[4:5], off
	global_load_dwordx4 v[80:83], v[14:15], off offset:64
	global_load_dwordx4 v[84:87], v[18:19], off offset:64
	global_load_dwordx4 v[88:91], v[16:17], off offset:64
	global_load_dwordx4 v[92:95], v[4:5], off offset:64
	global_load_dwordx4 v[96:99], v[14:15], off offset:128
	global_load_dwordx4 v[100:103], v[18:19], off offset:128
	global_load_dwordx4 v[104:107], v[16:17], off offset:128
	global_load_dwordx4 v[108:111], v[4:5], off offset:128
	global_load_dwordx4 v[112:115], v[14:15], off offset:192
	global_load_dwordx4 v[116:119], v[18:19], off offset:192
	global_load_dwordx4 v[120:123], v[16:17], off offset:192
	global_load_dwordx4 v[124:127], v[4:5], off offset:192
	global_load_dwordx4 v[128:131], v[14:15], off offset:256
	global_load_dwordx4 v[132:135], v[18:19], off offset:256
	global_load_dwordx4 v[136:139], v[16:17], off offset:256
	global_load_dwordx4 v[140:143], v[4:5], off offset:256
	global_load_dwordx4 v[144:147], v[14:15], off offset:320
	global_load_dwordx4 v[148:151], v[18:19], off offset:320
	global_load_dwordx4 v[152:155], v[16:17], off offset:320
	global_load_dwordx4 v[156:159], v[4:5], off offset:320
	global_load_dwordx4 v[160:163], v[14:15], off offset:384
	global_load_dwordx4 v[164:167], v[18:19], off offset:384
	global_load_dwordx4 v[168:171], v[16:17], off offset:384
	global_load_dwordx4 v[172:175], v[4:5], off offset:384
	s_waitcnt vmcnt(12)
	ds_bpermute_b32 v64, v199, v64
	ds_bpermute_b32 v65, v199, v65
	ds_bpermute_b32 v66, v199, v66
	ds_bpermute_b32 v67, v199, v67
	ds_bpermute_b32 v68, v199, v68
	ds_bpermute_b32 v69, v199, v69
	ds_bpermute_b32 v70, v199, v70
	ds_bpermute_b32 v71, v199, v71
	ds_bpermute_b32 v72, v199, v72
	ds_bpermute_b32 v73, v199, v73
	ds_bpermute_b32 v74, v199, v74
	ds_bpermute_b32 v75, v199, v75
	ds_bpermute_b32 v76, v199, v76
	ds_bpermute_b32 v77, v199, v77
	ds_bpermute_b32 v78, v199, v78
	ds_bpermute_b32 v79, v199, v79
	s_waitcnt lgkmcnt(0)
	ds_bpermute_b32 v80, v199, v80
	ds_bpermute_b32 v81, v199, v81
	ds_bpermute_b32 v82, v199, v82
	ds_bpermute_b32 v83, v199, v83
	ds_bpermute_b32 v84, v199, v84
	ds_bpermute_b32 v85, v199, v85
	ds_bpermute_b32 v86, v199, v86
	ds_bpermute_b32 v87, v199, v87
	ds_bpermute_b32 v88, v199, v88
	ds_bpermute_b32 v89, v199, v89
	ds_bpermute_b32 v90, v199, v90
	ds_bpermute_b32 v91, v199, v91
	ds_bpermute_b32 v92, v199, v92
	ds_bpermute_b32 v93, v199, v93
	ds_bpermute_b32 v94, v199, v94
	ds_bpermute_b32 v95, v199, v95
	s_waitcnt lgkmcnt(0)
	ds_bpermute_b32 v96, v199, v96
	ds_bpermute_b32 v97, v199, v97
	ds_bpermute_b32 v98, v199, v98
	ds_bpermute_b32 v99, v199, v99
	ds_bpermute_b32 v100, v199, v100
	ds_bpermute_b32 v101, v199, v101
	ds_bpermute_b32 v102, v199, v102
	ds_bpermute_b32 v103, v199, v103
	ds_bpermute_b32 v104, v199, v104
	ds_bpermute_b32 v105, v199, v105
	ds_bpermute_b32 v106, v199, v106
	ds_bpermute_b32 v107, v199, v107
	ds_bpermute_b32 v108, v199, v108
	ds_bpermute_b32 v109, v199, v109
	ds_bpermute_b32 v110, v199, v110
	ds_bpermute_b32 v111, v199, v111
	s_waitcnt lgkmcnt(0)
	ds_bpermute_b32 v112, v199, v112
	ds_bpermute_b32 v113, v199, v113
	ds_bpermute_b32 v114, v199, v114
	ds_bpermute_b32 v115, v199, v115
	ds_bpermute_b32 v116, v199, v116
	ds_bpermute_b32 v117, v199, v117
	ds_bpermute_b32 v118, v199, v118
	ds_bpermute_b32 v119, v199, v119
	ds_bpermute_b32 v120, v199, v120
	ds_bpermute_b32 v121, v199, v121
	ds_bpermute_b32 v122, v199, v122
	ds_bpermute_b32 v123, v199, v123
	ds_bpermute_b32 v124, v199, v124
	ds_bpermute_b32 v125, v199, v125
	ds_bpermute_b32 v126, v199, v126
	ds_bpermute_b32 v127, v199, v127
	s_waitcnt lgkmcnt(0)
	v_mfma_f32_16x16x32_bf16 v[38:41], v[64:67], v[72:75], 0
	v_mfma_f32_16x16x32_bf16 v[26:29], v[64:67], v[76:79], 0
	v_mfma_f32_16x16x32_bf16 v[30:33], v[68:71], v[72:75], 0
	v_mfma_f32_16x16x32_bf16 v[34:37], v[68:71], v[76:79], 0
	v_mfma_f32_16x16x32_bf16 v[38:41], v[80:83], v[88:91], v[38:41]
	v_mfma_f32_16x16x32_bf16 v[26:29], v[80:83], v[92:95], v[26:29]
	v_mfma_f32_16x16x32_bf16 v[30:33], v[84:87], v[88:91], v[30:33]
	v_mfma_f32_16x16x32_bf16 v[34:37], v[84:87], v[92:95], v[34:37]
	v_mfma_f32_16x16x32_bf16 v[38:41], v[96:99], v[104:107], v[38:41]
	v_mfma_f32_16x16x32_bf16 v[26:29], v[96:99], v[108:111], v[26:29]
	v_mfma_f32_16x16x32_bf16 v[30:33], v[100:103], v[104:107], v[30:33]
	v_mfma_f32_16x16x32_bf16 v[34:37], v[100:103], v[108:111], v[34:37]
	v_mfma_f32_16x16x32_bf16 v[38:41], v[112:115], v[120:123], v[38:41]
	v_mfma_f32_16x16x32_bf16 v[26:29], v[112:115], v[124:127], v[26:29]
	v_mfma_f32_16x16x32_bf16 v[30:33], v[116:119], v[120:123], v[30:33]
	v_mfma_f32_16x16x32_bf16 v[34:37], v[116:119], v[124:127], v[34:37]
	global_load_dwordx4 v[64:67], v[14:15], off offset:448
	global_load_dwordx4 v[68:71], v[18:19], off offset:448
	global_load_dwordx4 v[72:75], v[16:17], off offset:448
	global_load_dwordx4 v[76:79], v[4:5], off offset:448
	global_load_dwordx4 v[80:83], v[14:15], off offset:512
	global_load_dwordx4 v[84:87], v[18:19], off offset:512
	global_load_dwordx4 v[88:91], v[16:17], off offset:512
	global_load_dwordx4 v[92:95], v[4:5], off offset:512
	global_load_dwordx4 v[96:99], v[14:15], off offset:576
	global_load_dwordx4 v[100:103], v[18:19], off offset:576
	global_load_dwordx4 v[104:107], v[16:17], off offset:576
	global_load_dwordx4 v[108:111], v[4:5], off offset:576
	global_load_dwordx4 v[112:115], v[14:15], off offset:640
	global_load_dwordx4 v[116:119], v[18:19], off offset:640
	global_load_dwordx4 v[120:123], v[16:17], off offset:640
	global_load_dwordx4 v[124:127], v[4:5], off offset:640
	s_waitcnt vmcnt(16)
	ds_bpermute_b32 v128, v199, v128
	ds_bpermute_b32 v129, v199, v129
	ds_bpermute_b32 v130, v199, v130
	ds_bpermute_b32 v131, v199, v131
	ds_bpermute_b32 v132, v199, v132
	ds_bpermute_b32 v133, v199, v133
	ds_bpermute_b32 v134, v199, v134
	ds_bpermute_b32 v135, v199, v135
	ds_bpermute_b32 v136, v199, v136
	ds_bpermute_b32 v137, v199, v137
	ds_bpermute_b32 v138, v199, v138
	ds_bpermute_b32 v139, v199, v139
	ds_bpermute_b32 v140, v199, v140
	ds_bpermute_b32 v141, v199, v141
	ds_bpermute_b32 v142, v199, v142
	ds_bpermute_b32 v143, v199, v143
	s_waitcnt lgkmcnt(0)
	ds_bpermute_b32 v144, v199, v144
	ds_bpermute_b32 v145, v199, v145
	ds_bpermute_b32 v146, v199, v146
	ds_bpermute_b32 v147, v199, v147
	ds_bpermute_b32 v148, v199, v148
	ds_bpermute_b32 v149, v199, v149
	ds_bpermute_b32 v150, v199, v150
	ds_bpermute_b32 v151, v199, v151
	ds_bpermute_b32 v152, v199, v152
	ds_bpermute_b32 v153, v199, v153
	ds_bpermute_b32 v154, v199, v154
	ds_bpermute_b32 v155, v199, v155
	ds_bpermute_b32 v156, v199, v156
	ds_bpermute_b32 v157, v199, v157
	ds_bpermute_b32 v158, v199, v158
	ds_bpermute_b32 v159, v199, v159
	s_waitcnt lgkmcnt(0)
	ds_bpermute_b32 v160, v199, v160
	ds_bpermute_b32 v161, v199, v161
	ds_bpermute_b32 v162, v199, v162
	ds_bpermute_b32 v163, v199, v163
	ds_bpermute_b32 v164, v199, v164
	ds_bpermute_b32 v165, v199, v165
	ds_bpermute_b32 v166, v199, v166
	ds_bpermute_b32 v167, v199, v167
	ds_bpermute_b32 v168, v199, v168
	ds_bpermute_b32 v169, v199, v169
	ds_bpermute_b32 v170, v199, v170
	ds_bpermute_b32 v171, v199, v171
	ds_bpermute_b32 v172, v199, v172
	ds_bpermute_b32 v173, v199, v173
	ds_bpermute_b32 v174, v199, v174
	ds_bpermute_b32 v175, v199, v175
	s_waitcnt lgkmcnt(0)
	v_mfma_f32_16x16x32_bf16 v[38:41], v[128:131], v[136:139], v[38:41]
	v_mfma_f32_16x16x32_bf16 v[26:29], v[128:131], v[140:143], v[26:29]
	v_mfma_f32_16x16x32_bf16 v[30:33], v[132:135], v[136:139], v[30:33]
	v_mfma_f32_16x16x32_bf16 v[34:37], v[132:135], v[140:143], v[34:37]
	v_mfma_f32_16x16x32_bf16 v[38:41], v[144:147], v[152:155], v[38:41]
	v_mfma_f32_16x16x32_bf16 v[26:29], v[144:147], v[156:159], v[26:29]
	v_mfma_f32_16x16x32_bf16 v[30:33], v[148:151], v[152:155], v[30:33]
	v_mfma_f32_16x16x32_bf16 v[34:37], v[148:151], v[156:159], v[34:37]
	v_mfma_f32_16x16x32_bf16 v[38:41], v[160:163], v[168:171], v[38:41]
	v_mfma_f32_16x16x32_bf16 v[26:29], v[160:163], v[172:175], v[26:29]
	v_mfma_f32_16x16x32_bf16 v[30:33], v[164:167], v[168:171], v[30:33]
	v_mfma_f32_16x16x32_bf16 v[34:37], v[164:167], v[172:175], v[34:37]
	global_load_dwordx4 v[128:131], v[14:15], off offset:704
	global_load_dwordx4 v[132:135], v[18:19], off offset:704
	global_load_dwordx4 v[136:139], v[16:17], off offset:704
	global_load_dwordx4 v[140:143], v[4:5], off offset:704
	global_load_dwordx4 v[144:147], v[14:15], off offset:768
	global_load_dwordx4 v[148:151], v[18:19], off offset:768
	global_load_dwordx4 v[152:155], v[16:17], off offset:768
	global_load_dwordx4 v[156:159], v[4:5], off offset:768
	global_load_dwordx4 v[160:163], v[14:15], off offset:832
	global_load_dwordx4 v[164:167], v[18:19], off offset:832
	global_load_dwordx4 v[168:171], v[16:17], off offset:832
	global_load_dwordx4 v[172:175], v[4:5], off offset:832
	s_waitcnt vmcnt(12)
	ds_bpermute_b32 v64, v199, v64
	ds_bpermute_b32 v65, v199, v65
	ds_bpermute_b32 v66, v199, v66
	ds_bpermute_b32 v67, v199, v67
	ds_bpermute_b32 v68, v199, v68
	ds_bpermute_b32 v69, v199, v69
	ds_bpermute_b32 v70, v199, v70
	ds_bpermute_b32 v71, v199, v71
	ds_bpermute_b32 v72, v199, v72
	ds_bpermute_b32 v73, v199, v73
	ds_bpermute_b32 v74, v199, v74
	ds_bpermute_b32 v75, v199, v75
	ds_bpermute_b32 v76, v199, v76
	ds_bpermute_b32 v77, v199, v77
	ds_bpermute_b32 v78, v199, v78
	ds_bpermute_b32 v79, v199, v79
	s_waitcnt lgkmcnt(0)
	ds_bpermute_b32 v80, v199, v80
	ds_bpermute_b32 v81, v199, v81
	ds_bpermute_b32 v82, v199, v82
	ds_bpermute_b32 v83, v199, v83
	ds_bpermute_b32 v84, v199, v84
	ds_bpermute_b32 v85, v199, v85
	ds_bpermute_b32 v86, v199, v86
	ds_bpermute_b32 v87, v199, v87
	ds_bpermute_b32 v88, v199, v88
	ds_bpermute_b32 v89, v199, v89
	ds_bpermute_b32 v90, v199, v90
	ds_bpermute_b32 v91, v199, v91
	ds_bpermute_b32 v92, v199, v92
	ds_bpermute_b32 v93, v199, v93
	ds_bpermute_b32 v94, v199, v94
	ds_bpermute_b32 v95, v199, v95
	s_waitcnt lgkmcnt(0)
	ds_bpermute_b32 v96, v199, v96
	ds_bpermute_b32 v97, v199, v97
	ds_bpermute_b32 v98, v199, v98
	ds_bpermute_b32 v99, v199, v99
	ds_bpermute_b32 v100, v199, v100
	ds_bpermute_b32 v101, v199, v101
	ds_bpermute_b32 v102, v199, v102
	ds_bpermute_b32 v103, v199, v103
	ds_bpermute_b32 v104, v199, v104
	ds_bpermute_b32 v105, v199, v105
	ds_bpermute_b32 v106, v199, v106
	ds_bpermute_b32 v107, v199, v107
	ds_bpermute_b32 v108, v199, v108
	ds_bpermute_b32 v109, v199, v109
	ds_bpermute_b32 v110, v199, v110
	ds_bpermute_b32 v111, v199, v111
	s_waitcnt lgkmcnt(0)
	ds_bpermute_b32 v112, v199, v112
	ds_bpermute_b32 v113, v199, v113
	ds_bpermute_b32 v114, v199, v114
	ds_bpermute_b32 v115, v199, v115
	ds_bpermute_b32 v116, v199, v116
	ds_bpermute_b32 v117, v199, v117
	ds_bpermute_b32 v118, v199, v118
	ds_bpermute_b32 v119, v199, v119
	ds_bpermute_b32 v120, v199, v120
	ds_bpermute_b32 v121, v199, v121
	ds_bpermute_b32 v122, v199, v122
	ds_bpermute_b32 v123, v199, v123
	ds_bpermute_b32 v124, v199, v124
	ds_bpermute_b32 v125, v199, v125
	ds_bpermute_b32 v126, v199, v126
	ds_bpermute_b32 v127, v199, v127
	s_waitcnt lgkmcnt(0)
	v_mfma_f32_16x16x32_bf16 v[38:41], v[64:67], v[72:75], v[38:41]
	v_mfma_f32_16x16x32_bf16 v[26:29], v[64:67], v[76:79], v[26:29]
	v_mfma_f32_16x16x32_bf16 v[30:33], v[68:71], v[72:75], v[30:33]
	v_mfma_f32_16x16x32_bf16 v[34:37], v[68:71], v[76:79], v[34:37]
	v_mfma_f32_16x16x32_bf16 v[38:41], v[80:83], v[88:91], v[38:41]
	v_mfma_f32_16x16x32_bf16 v[26:29], v[80:83], v[92:95], v[26:29]
	v_mfma_f32_16x16x32_bf16 v[30:33], v[84:87], v[88:91], v[30:33]
	v_mfma_f32_16x16x32_bf16 v[34:37], v[84:87], v[92:95], v[34:37]
	v_mfma_f32_16x16x32_bf16 v[38:41], v[96:99], v[104:107], v[38:41]
	v_mfma_f32_16x16x32_bf16 v[26:29], v[96:99], v[108:111], v[26:29]
	v_mfma_f32_16x16x32_bf16 v[30:33], v[100:103], v[104:107], v[30:33]
	v_mfma_f32_16x16x32_bf16 v[34:37], v[100:103], v[108:111], v[34:37]
	v_mfma_f32_16x16x32_bf16 v[38:41], v[112:115], v[120:123], v[38:41]
	v_mfma_f32_16x16x32_bf16 v[26:29], v[112:115], v[124:127], v[26:29]
	v_mfma_f32_16x16x32_bf16 v[30:33], v[116:119], v[120:123], v[30:33]
	v_mfma_f32_16x16x32_bf16 v[34:37], v[116:119], v[124:127], v[34:37]
	global_load_dwordx4 v[64:67], v[14:15], off offset:896
	global_load_dwordx4 v[68:71], v[18:19], off offset:896
	global_load_dwordx4 v[72:75], v[16:17], off offset:896
	global_load_dwordx4 v[76:79], v[4:5], off offset:896
	global_load_dwordx4 v[80:83], v[14:15], off offset:960
	global_load_dwordx4 v[84:87], v[18:19], off offset:960
	global_load_dwordx4 v[88:91], v[16:17], off offset:960
	global_load_dwordx4 v[92:95], v[4:5], off offset:960
	s_waitcnt vmcnt(8)
	ds_bpermute_b32 v128, v199, v128
	ds_bpermute_b32 v129, v199, v129
	ds_bpermute_b32 v130, v199, v130
	ds_bpermute_b32 v131, v199, v131
	ds_bpermute_b32 v132, v199, v132
	ds_bpermute_b32 v133, v199, v133
	ds_bpermute_b32 v134, v199, v134
	ds_bpermute_b32 v135, v199, v135
	ds_bpermute_b32 v136, v199, v136
	ds_bpermute_b32 v137, v199, v137
	ds_bpermute_b32 v138, v199, v138
	ds_bpermute_b32 v139, v199, v139
	ds_bpermute_b32 v140, v199, v140
	ds_bpermute_b32 v141, v199, v141
	ds_bpermute_b32 v142, v199, v142
	ds_bpermute_b32 v143, v199, v143
	s_waitcnt lgkmcnt(0)
	ds_bpermute_b32 v144, v199, v144
	ds_bpermute_b32 v145, v199, v145
	ds_bpermute_b32 v146, v199, v146
	ds_bpermute_b32 v147, v199, v147
	ds_bpermute_b32 v148, v199, v148
	ds_bpermute_b32 v149, v199, v149
	ds_bpermute_b32 v150, v199, v150
	ds_bpermute_b32 v151, v199, v151
	ds_bpermute_b32 v152, v199, v152
	ds_bpermute_b32 v153, v199, v153
	ds_bpermute_b32 v154, v199, v154
	ds_bpermute_b32 v155, v199, v155
	ds_bpermute_b32 v156, v199, v156
	ds_bpermute_b32 v157, v199, v157
	ds_bpermute_b32 v158, v199, v158
	ds_bpermute_b32 v159, v199, v159
	s_waitcnt lgkmcnt(0)
	ds_bpermute_b32 v160, v199, v160
	ds_bpermute_b32 v161, v199, v161
	ds_bpermute_b32 v162, v199, v162
	ds_bpermute_b32 v163, v199, v163
	ds_bpermute_b32 v164, v199, v164
	ds_bpermute_b32 v165, v199, v165
	ds_bpermute_b32 v166, v199, v166
	ds_bpermute_b32 v167, v199, v167
	ds_bpermute_b32 v168, v199, v168
	ds_bpermute_b32 v169, v199, v169
	ds_bpermute_b32 v170, v199, v170
	ds_bpermute_b32 v171, v199, v171
	ds_bpermute_b32 v172, v199, v172
	ds_bpermute_b32 v173, v199, v173
	ds_bpermute_b32 v174, v199, v174
	ds_bpermute_b32 v175, v199, v175
	s_waitcnt lgkmcnt(0)
	v_mfma_f32_16x16x32_bf16 v[38:41], v[128:131], v[136:139], v[38:41]
	v_mfma_f32_16x16x32_bf16 v[26:29], v[128:131], v[140:143], v[26:29]
	v_mfma_f32_16x16x32_bf16 v[30:33], v[132:135], v[136:139], v[30:33]
	v_mfma_f32_16x16x32_bf16 v[34:37], v[132:135], v[140:143], v[34:37]
	v_mfma_f32_16x16x32_bf16 v[38:41], v[144:147], v[152:155], v[38:41]
	v_mfma_f32_16x16x32_bf16 v[26:29], v[144:147], v[156:159], v[26:29]
	v_mfma_f32_16x16x32_bf16 v[30:33], v[148:151], v[152:155], v[30:33]
	v_mfma_f32_16x16x32_bf16 v[34:37], v[148:151], v[156:159], v[34:37]
	v_mfma_f32_16x16x32_bf16 v[38:41], v[160:163], v[168:171], v[38:41]
	v_mfma_f32_16x16x32_bf16 v[26:29], v[160:163], v[172:175], v[26:29]
	v_mfma_f32_16x16x32_bf16 v[30:33], v[164:167], v[168:171], v[30:33]
	v_mfma_f32_16x16x32_bf16 v[34:37], v[164:167], v[172:175], v[34:37]
	s_waitcnt vmcnt(0)
	ds_bpermute_b32 v64, v199, v64
	ds_bpermute_b32 v65, v199, v65
	ds_bpermute_b32 v66, v199, v66
	ds_bpermute_b32 v67, v199, v67
	ds_bpermute_b32 v68, v199, v68
	ds_bpermute_b32 v69, v199, v69
	ds_bpermute_b32 v70, v199, v70
	ds_bpermute_b32 v71, v199, v71
	ds_bpermute_b32 v72, v199, v72
	ds_bpermute_b32 v73, v199, v73
	ds_bpermute_b32 v74, v199, v74
	ds_bpermute_b32 v75, v199, v75
	ds_bpermute_b32 v76, v199, v76
	ds_bpermute_b32 v77, v199, v77
	ds_bpermute_b32 v78, v199, v78
	ds_bpermute_b32 v79, v199, v79
	s_waitcnt lgkmcnt(0)
	ds_bpermute_b32 v80, v199, v80
	ds_bpermute_b32 v81, v199, v81
	ds_bpermute_b32 v82, v199, v82
	ds_bpermute_b32 v83, v199, v83
	ds_bpermute_b32 v84, v199, v84
	ds_bpermute_b32 v85, v199, v85
	ds_bpermute_b32 v86, v199, v86
	ds_bpermute_b32 v87, v199, v87
	ds_bpermute_b32 v88, v199, v88
	ds_bpermute_b32 v89, v199, v89
	ds_bpermute_b32 v90, v199, v90
	ds_bpermute_b32 v91, v199, v91
	ds_bpermute_b32 v92, v199, v92
	ds_bpermute_b32 v93, v199, v93
	ds_bpermute_b32 v94, v199, v94
	ds_bpermute_b32 v95, v199, v95
	s_waitcnt lgkmcnt(0)
	v_mfma_f32_16x16x32_bf16 v[38:41], v[64:67], v[72:75], v[38:41]
	v_mfma_f32_16x16x32_bf16 v[26:29], v[64:67], v[76:79], v[26:29]
	v_mfma_f32_16x16x32_bf16 v[30:33], v[68:71], v[72:75], v[30:33]
	v_mfma_f32_16x16x32_bf16 v[34:37], v[68:71], v[76:79], v[34:37]
	v_mfma_f32_16x16x32_bf16 v[38:41], v[80:83], v[88:91], v[38:41]
	v_mfma_f32_16x16x32_bf16 v[26:29], v[80:83], v[92:95], v[26:29]
	v_mfma_f32_16x16x32_bf16 v[30:33], v[84:87], v[88:91], v[30:33]
	v_mfma_f32_16x16x32_bf16 v[34:37], v[84:87], v[92:95], v[34:37]
	v_add_u32_e32 v4, s19, v21
	s_nop 7
	s_nop 1
	ds_write_b128 v4, v[38:41]
	ds_write_b128 v4, v[30:33] offset:1024
	ds_write_b128 v4, v[26:29] offset:2048
	ds_write_b128 v4, v[34:37] offset:3072
	s_waitcnt lgkmcnt(0)
	s_barrier
	s_and_saveexec_b64 s[42:43], s[0:1]
	s_cbranch_execz .LBB0_1085
	v_lshlrev_b32_e32 v18, 16, v2
	v_and_b32_e32 v19, 0xffff0000, v2
	v_lshlrev_b32_e32 v26, 16, v3
	v_and_b32_e32 v27, 0xffff0000, v3
	ds_read_b128 v[2:5], v22
	ds_read_b128 v[14:17], v23 offset:4096
	s_andn2_b64 vcc, exec, s[38:39]
	s_waitcnt lgkmcnt(0)
	v_pk_add_f32 v[16:17], v[4:5], v[16:17]
	v_pk_add_f32 v[14:15], v[2:3], v[14:15]
	ds_read_b128 v[2:5], v23 offset:8192
	s_waitcnt lgkmcnt(0)
	v_pk_add_f32 v[16:17], v[16:17], v[4:5]
	v_pk_add_f32 v[14:15], v[14:15], v[2:3]
	ds_read_b128 v[2:5], v23 offset:12288
	s_waitcnt lgkmcnt(0)
	v_pk_add_f32 v[16:17], v[16:17], v[4:5]
	v_pk_add_f32 v[14:15], v[14:15], v[2:3]
	ds_read_b128 v[2:5], v23 offset:16384
	s_waitcnt lgkmcnt(0)
	v_pk_add_f32 v[16:17], v[16:17], v[4:5]
	v_pk_add_f32 v[14:15], v[14:15], v[2:3]
	ds_read_b128 v[2:5], v23 offset:20480
	s_waitcnt lgkmcnt(0)
	v_pk_add_f32 v[16:17], v[16:17], v[4:5]
	v_pk_add_f32 v[14:15], v[14:15], v[2:3]
	ds_read_b128 v[2:5], v23 offset:24576
	s_waitcnt lgkmcnt(0)
	v_pk_add_f32 v[16:17], v[16:17], v[4:5]
	v_pk_add_f32 v[14:15], v[14:15], v[2:3]
	ds_read_b128 v[2:5], v23 offset:28672
	s_waitcnt lgkmcnt(0)
	v_pk_add_f32 v[4:5], v[16:17], v[4:5]
	v_pk_add_f32 v[2:3], v[14:15], v[2:3]
	v_pk_add_f32 v[4:5], v[4:5], v[26:27]
	v_pk_add_f32 v[2:3], v[2:3], v[18:19]
	s_cbranch_vccnz .LBB0_1091
	v_lshlrev_b64 v[14:15], 12, v[10:11]
	v_lshl_add_u64 v[14:15], s[52:53], 0, v[14:15]
	v_lshl_add_u64 v[14:15], v[12:13], 2, v[14:15]
	global_store_dwordx4 v[14:15], v[2:5], off
